# group barriers: single-XCD groups (nx==1) skip the cross-XCD TOP/TOPGEN atomics on the last arriver's path
# speedup vs baseline: 1.0158x; 1.0065x over previous
; __device__ __forceinline__ unsigned xb_ld(unsigned* p)              { return __hip_atomic_load(p, __ATOMIC_RELAXED, __HIP_MEMORY_SCOPE_AGENT); }
; __device__ __forceinline__ unsigned xb_add(unsigned* p, unsigned v) { return __hip_atomic_fetch_add(p, v, __ATOMIC_RELAXED, __HIP_MEMORY_SCOPE_AGENT); }
; #define XB_SPIN(cond, bar) do { unsigned _sp = 0; while (cond) { __builtin_amdgcn_s_sleep(1); \
;     if ((++_sp & 255u) == 0u) { if (xb_ld(&(bar)[XB_TMO])) break; if (_sp > XB_SPIN_CAP) { atomicAdd(&(bar)[XB_TMO], 1u); break; } } } } while (0)
; __device__ __forceinline__ void xcd_barrier(const XcdBarrier& b) {
;     ...
;         const unsigned old = xb_add(&bar[XB_XSUB(b.x)], 1u);
;         const unsigned gen = old / nloc;
;         if (old + 1u == (gen + 1u) * nloc) {
;             __builtin_amdgcn_fence(__ATOMIC_RELEASE, "agent");
;             asm volatile("s_waitcnt vmcnt(0)" ::: "memory");
;             const unsigned og = xb_add(&bar[XB_TOP], 1u);
;             const unsigned tg = og / nx;
;             if (og + 1u == (tg + 1u) * nx) xb_add(&bar[XB_TOPGEN], 1u);
;             else XB_SPIN(xb_ld(&bar[XB_TOPGEN]) == tg, bar);
.LBB0_498:
	s_andn2_saveexec_b64 s[8:9], s[8:9]
	s_cbranch_execz .LBB0_516
	s_mov_b64 s[8:9], exec
	buffer_wbl2 sc1
	s_waitcnt lgkmcnt(0)
	s_waitcnt vmcnt(0)
	v_cmp_eq_u32_e32 vcc, 1, v0
	s_cbranch_vccnz .Lgb_skip_0
	v_mbcnt_lo_u32_b32 v1, s8, 0
	v_mbcnt_hi_u32_b32 v1, s9, v1
	v_cmp_eq_u32_e32 vcc, 0, v1
	s_and_saveexec_b64 s[12:13], vcc
	s_cbranch_execz .LBB0_501
	s_bcnt1_i32_b64 s8, s[8:9]
	v_mov_b32_e32 v2, 0x3000
	v_mov_b32_e32 v3, s8
	global_atomic_add v2, v2, v3, s[60:61] offset:1024 sc0

; __device__ __forceinline__ unsigned xb_add(unsigned* p, unsigned v) { return __hip_atomic_fetch_add(p, v, __ATOMIC_RELAXED, __HIP_MEMORY_SCOPE_AGENT); }
; __device__ __forceinline__ void xcd_barrier(const XcdBarrier& b) {
;     ...
;             __builtin_amdgcn_fence(__ATOMIC_ACQUIRE, "agent");
;             xb_add(&bar[XB_XGEN(b.x)], 1u);
;             asm volatile("s_waitcnt vmcnt(0)" ::: "memory");
.Lgb_skip_0:
	v_mov_b32_e32 v0, 0x2000
	v_mov_b32_e32 v1, 1
	s_waitcnt vmcnt(0)
	buffer_inv sc1
	global_atomic_add v0, v1, s[6:7] offset:1024
	s_waitcnt vmcnt(0)

; __device__ __forceinline__ unsigned xb_ld(unsigned* p)              { return __hip_atomic_load(p, __ATOMIC_RELAXED, __HIP_MEMORY_SCOPE_AGENT); }
; __device__ __forceinline__ unsigned xb_add(unsigned* p, unsigned v) { return __hip_atomic_fetch_add(p, v, __ATOMIC_RELAXED, __HIP_MEMORY_SCOPE_AGENT); }
; #define XB_SPIN(cond, bar) do { unsigned _sp = 0; while (cond) { __builtin_amdgcn_s_sleep(1); \
;     if ((++_sp & 255u) == 0u) { if (xb_ld(&(bar)[XB_TMO])) break; if (_sp > XB_SPIN_CAP) { atomicAdd(&(bar)[XB_TMO], 1u); break; } } } } while (0)
; __device__ __forceinline__ void xcd_barrier(const XcdBarrier& b) {
;     ...
;         const unsigned old = xb_add(&bar[XB_XSUB(b.x)], 1u);
;         const unsigned gen = old / nloc;
;         if (old + 1u == (gen + 1u) * nloc) {
;             __builtin_amdgcn_fence(__ATOMIC_RELEASE, "agent");
;             asm volatile("s_waitcnt vmcnt(0)" ::: "memory");
;             const unsigned og = xb_add(&bar[XB_TOP], 1u);
;             const unsigned tg = og / nx;
;             if (og + 1u == (tg + 1u) * nx) xb_add(&bar[XB_TOPGEN], 1u);
;             else XB_SPIN(xb_ld(&bar[XB_TOPGEN]) == tg, bar);
.LBB0_762:
	s_andn2_saveexec_b64 s[6:7], s[6:7]
	s_cbranch_execz .LBB0_788
	s_mov_b64 s[6:7], exec
	buffer_wbl2 sc1
	s_waitcnt lgkmcnt(0)
	s_waitcnt vmcnt(0)
	v_cmp_eq_u32_e32 vcc, 1, v0
	s_cbranch_vccnz .Lgb_skip_1
	v_mbcnt_lo_u32_b32 v1, s6, 0
	v_mbcnt_hi_u32_b32 v1, s7, v1
	v_cmp_eq_u32_e32 vcc, 0, v1
	s_and_saveexec_b64 s[8:9], vcc
	s_cbranch_execz .LBB0_765
	s_bcnt1_i32_b64 s6, s[6:7]
	v_mov_b32_e32 v2, 0x3000
	v_mov_b32_e32 v3, s6
	global_atomic_add v2, v2, v3, s[60:61] offset:1024 sc0

; __device__ __forceinline__ unsigned xb_add(unsigned* p, unsigned v) { return __hip_atomic_fetch_add(p, v, __ATOMIC_RELAXED, __HIP_MEMORY_SCOPE_AGENT); }
; __device__ __forceinline__ void xcd_barrier(const XcdBarrier& b) {
;     ...
;             __builtin_amdgcn_fence(__ATOMIC_ACQUIRE, "agent");
;             xb_add(&bar[XB_XGEN(b.x)], 1u);
;             asm volatile("s_waitcnt vmcnt(0)" ::: "memory");
.Lgb_skip_1:
	v_mov_b32_e32 v0, 0x2000
	v_mov_b32_e32 v1, 1
	s_waitcnt vmcnt(0)
	buffer_inv sc1
	global_atomic_add v0, v1, s[4:5] offset:1024
	s_waitcnt vmcnt(0)
